# P0 LayerNorm(mem) gamma/beta hoisted and x->bf16 batched; P5a rows rebalanced away from the 8 workgroups carrying the sample P5b item
# speedup vs baseline: 1.0019x; 1.0019x over previous
; __device__ __forceinline__ unsigned cvt_pk_bf16(float lo, float hi) { unsigned r; asm volatile("v_cvt_pk_bf16_f32 %0, %1, %2" : "=v"(r) : "v"(lo), "v"(hi)); return r; }
; __global__ void __launch_bounds__(NTHREADS, 2) fwd_kernel(Params P) {
;     ...
;         for (size_t i = (size_t)gw * 64 + lane; i < (size_t)MPAD * D / 8; i += (size_t)NGW * 64) {
;             const size_t e = i * 8; const int r = (int)(e / D);
;             u32x4 w = (u32x4){0u, 0u, 0u, 0u};
;             if (r < MR) { const float* src = (r < MP) ? P.in[I_XP] + e : P.in[I_XS] + (e - (size_t)MP * D);
;                 const f32x4 a = __builtin_nontemporal_load((const f32x4*)src), b = __builtin_nontemporal_load((const f32x4*)(src + 4));
;                 w.x = cvt_pk_bf16(a[0], a[1]); w.y = cvt_pk_bf16(a[2], a[3]); w.z = cvt_pk_bf16(b[0], b[1]); w.w = cvt_pk_bf16(b[2], b[3]); }
;             *(u32x4*)(XB + e) = w;
;         }
.LBB0_65:
	s_or_b64 exec, exec, s[4:5]
	s_ashr_i32 s31, s30, 31
	v_lshlrev_b32_e32 v176, 4, v237
	v_mov_b32_e32 v177, 0
	s_ashr_i32 s87, s86, 31
	v_readlane_b32 s52, v254, 45
	v_readlane_b32 s53, v254, 46
	v_readlane_b32 s60, v254, 47
	v_readlane_b32 s61, v254, 48
	s_add_u32 s54, s92, 0xcca0000
	s_addc_u32 s55, s93, 0
	v_lshl_add_u32 v2, s34, 9, v178
	v_lshlrev_b32_e32 v3, 5, v2
	v_lshlrev_b32_e32 v4, 4, v2
	s_nop 4
	global_load_dwordx4 v[16:19], v3, s[52:53] nt
	global_load_dwordx4 v[20:23], v3, s[52:53] offset:16 nt
	s_add_u32 s56, s52, 0x400000
	s_addc_u32 s57, s53, 0
	global_load_dwordx4 v[24:27], v3, s[56:57] nt
	global_load_dwordx4 v[28:31], v3, s[56:57] offset:16 nt
	s_add_u32 s56, s52, 0x800000
	s_addc_u32 s57, s53, 0
	global_load_dwordx4 v[32:35], v3, s[56:57] nt
	global_load_dwordx4 v[36:39], v3, s[56:57] offset:16 nt
	s_add_u32 s56, s52, 0xc00000
	s_addc_u32 s57, s53, 0
	global_load_dwordx4 v[40:43], v3, s[56:57] nt
	global_load_dwordx4 v[44:47], v3, s[56:57] offset:16 nt
	s_add_u32 s56, s52, 0x1000000
	s_addc_u32 s57, s53, 0
	global_load_dwordx4 v[48:51], v3, s[56:57] nt
	global_load_dwordx4 v[52:55], v3, s[56:57] offset:16 nt
	s_add_u32 s56, s52, 0x1400000
	s_addc_u32 s57, s53, 0
	global_load_dwordx4 v[56:59], v3, s[56:57] nt
	global_load_dwordx4 v[60:63], v3, s[56:57] offset:16 nt
	s_add_u32 s56, s52, 0x1800000
	s_addc_u32 s57, s53, 0
	global_load_dwordx4 v[64:67], v3, s[56:57] nt
	global_load_dwordx4 v[68:71], v3, s[56:57] offset:16 nt
	s_add_u32 s56, s52, 0x1c00000
	s_addc_u32 s57, s53, 0
	global_load_dwordx4 v[72:75], v3, s[56:57] nt
	global_load_dwordx4 v[76:79], v3, s[56:57] offset:16 nt
	s_waitcnt vmcnt(14)
	v_cvt_pk_bf16_f32 v16, v16, v17
	v_cvt_pk_bf16_f32 v17, v18, v19
	v_cvt_pk_bf16_f32 v18, v20, v21
	v_cvt_pk_bf16_f32 v19, v22, v23
	global_store_dwordx4 v4, v[16:19], s[54:55]
	s_waitcnt vmcnt(13)
	v_cvt_pk_bf16_f32 v24, v24, v25
	v_cvt_pk_bf16_f32 v25, v26, v27
	v_cvt_pk_bf16_f32 v26, v28, v29
	v_cvt_pk_bf16_f32 v27, v30, v31
	s_add_u32 s58, s54, 0x200000
	s_addc_u32 s59, s55, 0
	global_store_dwordx4 v4, v[24:27], s[58:59]
	s_waitcnt vmcnt(12)
	v_cvt_pk_bf16_f32 v32, v32, v33
	v_cvt_pk_bf16_f32 v33, v34, v35
	v_cvt_pk_bf16_f32 v34, v36, v37
	v_cvt_pk_bf16_f32 v35, v38, v39
	s_add_u32 s58, s54, 0x400000
	s_addc_u32 s59, s55, 0
	global_store_dwordx4 v4, v[32:35], s[58:59]
	s_waitcnt vmcnt(11)
	v_cvt_pk_bf16_f32 v40, v40, v41
	v_cvt_pk_bf16_f32 v41, v42, v43
	v_cvt_pk_bf16_f32 v42, v44, v45
	v_cvt_pk_bf16_f32 v43, v46, v47
	s_add_u32 s58, s54, 0x600000
	s_addc_u32 s59, s55, 0
	global_store_dwordx4 v4, v[40:43], s[58:59]
	s_waitcnt vmcnt(10)
	v_cvt_pk_bf16_f32 v48, v48, v49
	v_cvt_pk_bf16_f32 v49, v50, v51
	v_cvt_pk_bf16_f32 v50, v52, v53
	v_cvt_pk_bf16_f32 v51, v54, v55
	s_add_u32 s58, s54, 0x800000
	s_addc_u32 s59, s55, 0
	global_store_dwordx4 v4, v[48:51], s[58:59]
	s_waitcnt vmcnt(9)
	v_cvt_pk_bf16_f32 v56, v56, v57
	v_cvt_pk_bf16_f32 v57, v58, v59
	v_cvt_pk_bf16_f32 v58, v60, v61
	v_cvt_pk_bf16_f32 v59, v62, v63
	s_add_u32 s58, s54, 0xa00000
	s_addc_u32 s59, s55, 0
	global_store_dwordx4 v4, v[56:59], s[58:59]
	s_waitcnt vmcnt(8)
	v_cvt_pk_bf16_f32 v64, v64, v65
	v_cvt_pk_bf16_f32 v65, v66, v67
	v_cvt_pk_bf16_f32 v66, v68, v69
	v_cvt_pk_bf16_f32 v67, v70, v71
	s_add_u32 s58, s54, 0xc00000
	s_addc_u32 s59, s55, 0
	global_store_dwordx4 v4, v[64:67], s[58:59]
	s_waitcnt vmcnt(7)
	v_cvt_pk_bf16_f32 v72, v72, v73
	v_cvt_pk_bf16_f32 v73, v74, v75
	v_cvt_pk_bf16_f32 v74, v76, v77
	v_cvt_pk_bf16_f32 v75, v78, v79
	s_add_u32 s58, s54, 0xe00000
	s_addc_u32 s59, s55, 0
	global_store_dwordx4 v4, v[72:75], s[58:59]
	s_add_u32 s56, s52, 0x2000000
	s_addc_u32 s57, s53, 0
	global_load_dwordx4 v[16:19], v3, s[56:57] nt
	global_load_dwordx4 v[20:23], v3, s[56:57] offset:16 nt
	s_add_u32 s56, s52, 0x2400000
	s_addc_u32 s57, s53, 0
	global_load_dwordx4 v[24:27], v3, s[56:57] nt
	global_load_dwordx4 v[28:31], v3, s[56:57] offset:16 nt
	s_add_u32 s56, s52, 0x2800000
	s_addc_u32 s57, s53, 0
	global_load_dwordx4 v[32:35], v3, s[56:57] nt
	global_load_dwordx4 v[36:39], v3, s[56:57] offset:16 nt
	s_add_u32 s56, s52, 0x2c00000
	s_addc_u32 s57, s53, 0
	global_load_dwordx4 v[40:43], v3, s[56:57] nt
	global_load_dwordx4 v[44:47], v3, s[56:57] offset:16 nt
	s_add_u32 s56, s52, 0x3000000
	s_addc_u32 s57, s53, 0
	global_load_dwordx4 v[48:51], v3, s[56:57] nt
	global_load_dwordx4 v[52:55], v3, s[56:57] offset:16 nt
	s_add_u32 s56, s52, 0x3400000
	s_addc_u32 s57, s53, 0
	global_load_dwordx4 v[56:59], v3, s[56:57] nt
	global_load_dwordx4 v[60:63], v3, s[56:57] offset:16 nt
	s_add_u32 s56, s52, 0x3800000
	s_addc_u32 s57, s53, 0
	global_load_dwordx4 v[64:67], v3, s[56:57] nt
	global_load_dwordx4 v[68:71], v3, s[56:57] offset:16 nt
	s_add_u32 s56, s52, 0x3c00000
	s_addc_u32 s57, s53, 0
	global_load_dwordx4 v[72:75], v3, s[56:57] nt
	global_load_dwordx4 v[76:79], v3, s[56:57] offset:16 nt
	s_waitcnt vmcnt(14)
	v_cvt_pk_bf16_f32 v16, v16, v17
	v_cvt_pk_bf16_f32 v17, v18, v19
	v_cvt_pk_bf16_f32 v18, v20, v21
	v_cvt_pk_bf16_f32 v19, v22, v23
	s_add_u32 s58, s54, 0x1000000
	s_addc_u32 s59, s55, 0
	global_store_dwordx4 v4, v[16:19], s[58:59]
	s_waitcnt vmcnt(13)
	v_cvt_pk_bf16_f32 v24, v24, v25
	v_cvt_pk_bf16_f32 v25, v26, v27
	v_cvt_pk_bf16_f32 v26, v28, v29
	v_cvt_pk_bf16_f32 v27, v30, v31
	s_add_u32 s58, s54, 0x1200000
	s_addc_u32 s59, s55, 0
	global_store_dwordx4 v4, v[24:27], s[58:59]
	s_waitcnt vmcnt(12)
	v_cvt_pk_bf16_f32 v32, v32, v33
	v_cvt_pk_bf16_f32 v33, v34, v35
	v_cvt_pk_bf16_f32 v34, v36, v37
	v_cvt_pk_bf16_f32 v35, v38, v39
	s_add_u32 s58, s54, 0x1400000
	s_addc_u32 s59, s55, 0
	global_store_dwordx4 v4, v[32:35], s[58:59]
	s_waitcnt vmcnt(11)
	v_cvt_pk_bf16_f32 v40, v40, v41
	v_cvt_pk_bf16_f32 v41, v42, v43
	v_cvt_pk_bf16_f32 v42, v44, v45
	v_cvt_pk_bf16_f32 v43, v46, v47
	s_add_u32 s58, s54, 0x1600000
	s_addc_u32 s59, s55, 0
	global_store_dwordx4 v4, v[40:43], s[58:59]
	s_waitcnt vmcnt(10)
	v_cvt_pk_bf16_f32 v48, v48, v49
	v_cvt_pk_bf16_f32 v49, v50, v51
	v_cvt_pk_bf16_f32 v50, v52, v53
	v_cvt_pk_bf16_f32 v51, v54, v55
	s_add_u32 s58, s54, 0x1800000
	s_addc_u32 s59, s55, 0
	global_store_dwordx4 v4, v[48:51], s[58:59]
	s_waitcnt vmcnt(9)
	v_cvt_pk_bf16_f32 v56, v56, v57
	v_cvt_pk_bf16_f32 v57, v58, v59
	v_cvt_pk_bf16_f32 v58, v60, v61
	v_cvt_pk_bf16_f32 v59, v62, v63
	s_add_u32 s58, s54, 0x1a00000
	s_addc_u32 s59, s55, 0
	global_store_dwordx4 v4, v[56:59], s[58:59]
	s_waitcnt vmcnt(8)
	v_cvt_pk_bf16_f32 v64, v64, v65
	v_cvt_pk_bf16_f32 v65, v66, v67
	v_cvt_pk_bf16_f32 v66, v68, v69
	v_cvt_pk_bf16_f32 v67, v70, v71
	s_add_u32 s58, s54, 0x1c00000
	s_addc_u32 s59, s55, 0
	global_store_dwordx4 v4, v[64:67], s[58:59]
	s_waitcnt vmcnt(7)
	v_cvt_pk_bf16_f32 v72, v72, v73
	v_cvt_pk_bf16_f32 v73, v74, v75
	v_cvt_pk_bf16_f32 v74, v76, v77
	v_cvt_pk_bf16_f32 v75, v78, v79
	s_add_u32 s58, s54, 0x1e00000
	s_addc_u32 s59, s55, 0
	global_store_dwordx4 v4, v[72:75], s[58:59]
	s_cmp_lt_u32 s34, 128
	s_cbranch_scc0 .Lxb_done
; __device__ __forceinline__ unsigned cvt_pk_bf16(float lo, float hi) { unsigned r; asm volatile("v_cvt_pk_bf16_f32 %0, %1, %2" : "=v"(r) : "v"(lo), "v"(hi)); return r; }
; __device__ __forceinline__ void ln_row(const float* yrow, const float* g, const float* b, float* of, bf16_t* ob, int lane) {
;     f32x4 v[8]; float s = 0.f;
; #pragma unroll
;     for (int j = 0; j < 8; ++j) { v[j] = *(const f32x4*)(yrow + 4 * lane + 256 * j); s += (v[j][0] + v[j][1]) + (v[j][2] + v[j][3]); }
;     const float mean = wave_sum(s) * (1.f / D); float s2 = 0.f;
; #pragma unroll
;     for (int j = 0; j < 8; ++j) { v[j] = v[j] - mean; s2 += (v[j][0] * v[j][0] + v[j][1] * v[j][1]) + (v[j][2] * v[j][2] + v[j][3] * v[j][3]); }
;     const float rstd = 1.0f / sqrtf(wave_sum(s2) * (1.f / D) + LN_EPS);
; #pragma unroll
;     for (int j = 0; j < 8; ++j) {
;         const f32x4 gg = *(const f32x4*)(g + 4 * lane + 256 * j), bb = *(const f32x4*)(b + 4 * lane + 256 * j);
; __global__ void __launch_bounds__(NTHREADS, 2) fwd_kernel(Params P) {
;     ...
;         for (size_t i = (size_t)gw * 64 + lane; i < (size_t)MPAD * D / 8; i += (size_t)NGW * 64) {
;             const size_t e = i * 8; const int r = (int)(e / D);
;             u32x4 w = (u32x4){0u, 0u, 0u, 0u};
;             if (r < MR) { const float* src = (r < MP) ? P.in[I_XP] + e : P.in[I_XS] + (e - (size_t)MP * D);
;                 const f32x4 a = __builtin_nontemporal_load((const f32x4*)src), b = __builtin_nontemporal_load((const f32x4*)(src + 4));
;                 w.x = cvt_pk_bf16(a[0], a[1]); w.y = cvt_pk_bf16(a[2], a[3]); w.z = cvt_pk_bf16(b[0], b[1]); w.w = cvt_pk_bf16(b[2], b[3]); }
;             *(u32x4*)(XB + e) = w;
;         }
;         for (int r = gw; r < 1024; r += NGW) ln_row(P.in[I_MEM] + (size_t)r * D, P.in[I_MLNG], P.in[I_MLNB], nullptr, MEMLN + (size_t)r * D, lane);
	s_add_u32 s58, s54, 0x2000000
	s_addc_u32 s59, s55, 0
	s_cmp_lt_u32 s34, 64
	s_cbranch_scc0 .Lxb_zero
	global_load_dwordx4 v[16:19], v3, s[60:61] nt
	global_load_dwordx4 v[20:23], v3, s[60:61] offset:16 nt
	s_waitcnt vmcnt(0)
	v_cvt_pk_bf16_f32 v16, v16, v17
	v_cvt_pk_bf16_f32 v17, v18, v19
	v_cvt_pk_bf16_f32 v18, v20, v21
	v_cvt_pk_bf16_f32 v19, v22, v23
	global_store_dwordx4 v4, v[16:19], s[58:59]
	s_branch .Lxb_done
.Lxb_zero:
	s_nop 1
	v_mov_b32_e32 v16, 0
	v_mov_b32_e32 v17, 0
	v_mov_b32_e32 v18, 0
	v_mov_b32_e32 v19, 0
	global_store_dwordx4 v4, v[16:19], s[58:59]
.Lxb_done:
.LBB0_71:
	s_cmpk_gt_i32 s30, 0x3ff
	s_cbranch_scc1 .LBB0_74
	v_mbcnt_hi_u32_b32 v2, -1, v179
	v_and_b32_e32 v1, 64, v2
	v_add_u32_e32 v3, 64, v1
	v_xor_b32_e32 v1, 1, v2
	v_cmp_lt_i32_e32 vcc, v1, v3
	s_waitcnt lgkmcnt(1)
	v_xor_b32_e32 v4, 2, v2
	v_readlane_b32 s8, v254, 27
	v_cndmask_b32_e32 v1, v2, v1, vcc
	v_cmp_lt_i32_e32 vcc, v4, v3
	v_readlane_b32 s9, v254, 28
	v_readlane_b32 s10, v254, 29
	v_cndmask_b32_e32 v4, v2, v4, vcc
	v_lshlrev_b32_e32 v58, 2, v4
	v_xor_b32_e32 v4, 4, v2
	v_cmp_lt_i32_e32 vcc, v4, v3
	v_readlane_b32 s11, v254, 30
	s_mov_b64 s[0:1], s[8:9]
	v_cndmask_b32_e32 v4, v2, v4, vcc
	v_lshlrev_b32_e32 v59, 2, v4
	v_xor_b32_e32 v4, 8, v2
	v_cmp_lt_i32_e32 vcc, v4, v3
	v_mov_b32_e32 v177, 0
	s_mov_b64 s[2:3], s[10:11]
	v_cndmask_b32_e32 v4, v2, v4, vcc
	v_lshlrev_b32_e32 v60, 2, v4
	v_xor_b32_e32 v4, 16, v2
	v_lshl_add_u64 v[34:35], s[0:1], 0, v[176:177]
	v_lshl_add_u64 v[36:37], s[2:3], 0, v[176:177]
	s_mov_b64 s[2:3], 0x1400
	v_cmp_lt_i32_e32 vcc, v4, v3
	v_readlane_b32 s12, v254, 31
	v_readlane_b32 s13, v254, 32
	v_readlane_b32 s14, v254, 33
	v_readlane_b32 s15, v254, 34
	v_readlane_b32 s16, v254, 35
	v_readlane_b32 s17, v254, 36
	v_readlane_b32 s18, v254, 37
	v_readlane_b32 s19, v254, 38
	v_readlane_b32 s20, v254, 39
	v_readlane_b32 s21, v254, 40
	v_readlane_b32 s22, v254, 41
	v_readlane_b32 s23, v254, 42
	v_lshl_add_u64 v[42:43], v[34:35], 0, s[2:3]
	v_lshl_add_u64 v[44:45], v[36:37], 0, s[2:3]
	s_mov_b64 s[2:3], 0x1800
	v_cndmask_b32_e32 v4, v2, v4, vcc
	v_lshl_add_u64 v[46:47], v[34:35], 0, s[2:3]
	v_lshl_add_u64 v[48:49], v[36:37], 0, s[2:3]
	s_mov_b64 s[2:3], 0x1c00
	v_readlane_b32 s8, v254, 45
	v_lshlrev_b32_e32 v61, 2, v4
	v_xor_b32_e32 v4, 32, v2
	v_lshl_add_u64 v[50:51], v[34:35], 0, s[2:3]
	v_lshl_add_u64 v[52:53], v[36:37], 0, s[2:3]
	s_lshl_b64 s[2:3], s[30:31], 13
	v_readlane_b32 s12, v254, 49
	v_cmp_lt_i32_e32 vcc, v4, v3
	v_readlane_b32 s13, v254, 50
	s_add_u32 s2, s12, s2
	v_cndmask_b32_e32 v2, v2, v4, vcc
	s_addc_u32 s3, s13, s3
	v_lshlrev_b32_e32 v62, 2, v2
	s_mov_b64 s[0:1], 0x1000
	v_lshl_add_u64 v[2:3], s[2:3], 0, v[176:177]
	s_ashr_i32 s87, s86, 31
	v_lshl_add_u64 v[38:39], v[34:35], 0, s[0:1]
	v_lshl_add_u64 v[40:41], v[36:37], 0, s[0:1]
	v_lshl_add_u64 v[54:55], v[2:3], 0, s[0:1]
	s_lshl_b64 s[4:5], s[86:87], 13
	s_lshl_b64 s[0:1], s[30:31], 12
	s_add_u32 s0, s92, s0
	v_lshlrev_b32_e32 v2, 3, v237
	v_mov_b32_e32 v3, v177
	s_addc_u32 s1, s93, s1
	v_readlane_b32 s9, v254, 46
	v_lshl_add_u64 v[2:3], s[0:1], 0, v[2:3]
	s_mov_b64 s[0:1], 0x2a9a0000
	v_lshlrev_b32_e32 v1, 2, v1
	v_lshl_add_u64 v[56:57], v[2:3], 0, s[0:1]
	s_lshl_b64 s[8:9], s[86:87], 12
	v_mov_b32_e32 v63, 0x3727c5ac
	s_mov_b32 s2, 0xf800000
	v_mov_b32_e32 v64, 0x260
	s_mov_b32 s3, s30
	v_readlane_b32 s10, v254, 47
	v_readlane_b32 s11, v254, 48
	v_readlane_b32 s14, v254, 51
	v_readlane_b32 s15, v254, 52
	v_readlane_b32 s16, v254, 53
	v_readlane_b32 s17, v254, 54
	v_readlane_b32 s18, v254, 55
	v_readlane_b32 s19, v254, 56
	v_readlane_b32 s20, v254, 57
	v_readlane_b32 s21, v254, 58
	v_readlane_b32 s22, v254, 59
	v_readlane_b32 s23, v254, 60
	global_load_dwordx4 v[100:103], v[34:35], off
	global_load_dwordx4 v[104:107], v[36:37], off
	global_load_dwordx4 v[108:111], v[34:35], off offset:1024
	global_load_dwordx4 v[112:115], v[36:37], off offset:1024
	global_load_dwordx4 v[116:119], v[34:35], off offset:2048
	global_load_dwordx4 v[120:123], v[36:37], off offset:2048
	global_load_dwordx4 v[124:127], v[34:35], off offset:3072
	global_load_dwordx4 v[128:131], v[36:37], off offset:3072
	global_load_dwordx4 v[132:135], v[38:39], off
	global_load_dwordx4 v[136:139], v[40:41], off
	global_load_dwordx4 v[140:143], v[42:43], off
	global_load_dwordx4 v[144:147], v[44:45], off
	global_load_dwordx4 v[148:151], v[46:47], off
	global_load_dwordx4 v[152:155], v[48:49], off
	global_load_dwordx4 v[156:159], v[50:51], off
	global_load_dwordx4 v[160:163], v[52:53], off
	s_waitcnt vmcnt(0)
; __device__ __forceinline__ void ln_row(const float* yrow, const float* g, const float* b, float* of, bf16_t* ob, int lane) {
;     f32x4 v[8]; float s = 0.f;
; #pragma unroll
;     for (int j = 0; j < 8; ++j) { v[j] = *(const f32x4*)(yrow + 4 * lane + 256 * j); s += (v[j][0] + v[j][1]) + (v[j][2] + v[j][3]); }
;     const float mean = wave_sum(s) * (1.f / D); float s2 = 0.f;
; #pragma unroll
;     for (int j = 0; j < 8; ++j) { v[j] = v[j] - mean; s2 += (v[j][0] * v[j][0] + v[j][1] * v[j][1]) + (v[j][2] * v[j][2] + v[j][3] * v[j][3]); }
.LBB0_73:
	global_load_dwordx4 v[30:33], v[54:55], off offset:-4096
	global_load_dwordx4 v[26:29], v[54:55], off offset:-3072
	global_load_dwordx4 v[22:25], v[54:55], off offset:-2048
	global_load_dwordx4 v[18:21], v[54:55], off offset:-1024
	global_load_dwordx4 v[10:13], v[54:55], off
	global_load_dwordx4 v[6:9], v[54:55], off offset:1024
	global_load_dwordx4 v[14:17], v[54:55], off offset:2048
	s_waitcnt lgkmcnt(0)
	global_load_dwordx4 v[2:5], v[54:55], off offset:3072
	v_mov_b32_e32 v66, v100
	v_mov_b32_e32 v67, v101
	v_mov_b32_e32 v68, v102
	v_mov_b32_e32 v69, v103
	v_mov_b32_e32 v70, v104
	v_mov_b32_e32 v71, v105
	v_mov_b32_e32 v72, v106
	v_mov_b32_e32 v73, v107
	s_add_i32 s3, s3, s86
	v_lshl_add_u64 v[54:55], v[54:55], 0, s[4:5]
	s_cmpk_gt_i32 s3, 0x3ff
	s_waitcnt vmcnt(7)
	v_mov_b32_e32 v74, v30
	s_waitcnt vmcnt(6)
	v_mov_b32_e32 v75, v26
	v_mov_b32_e32 v76, v31
	v_mov_b32_e32 v77, v27
	v_mov_b32_e32 v78, v32
	v_mov_b32_e32 v79, v28
	v_mov_b32_e32 v80, v33
	v_mov_b32_e32 v81, v29
	s_waitcnt vmcnt(5)
	v_mov_b32_e32 v82, v23
	v_mov_b32_e32 v83, v24
	v_mov_b32_e32 v84, v22
	v_mov_b32_e32 v85, v25
	v_pk_add_f32 v[74:75], v[74:75], v[76:77]
	v_pk_add_f32 v[76:77], v[78:79], v[80:81]
	v_pk_add_f32 v[78:79], v[82:83], v[84:85]
	v_pk_add_f32 v[74:75], v[74:75], v[76:77]
	v_pk_add_f32 v[76:77], v[78:79], v[78:79] op_sel:[0,1] op_sel_hi:[1,0]
	v_add_f32_e32 v65, 0, v74
	s_waitcnt vmcnt(4)
	v_add_f32_e32 v86, v18, v19
	v_add_f32_e32 v88, v20, v21
	s_waitcnt vmcnt(3)
	v_mov_b32_e32 v87, v12
	v_mov_b32_e32 v89, v13
	v_mov_b32_e32 v99, v10
	v_mov_b32_e32 v77, v11
	v_add_f32_e32 v98, v65, v75
	s_waitcnt vmcnt(2)
	v_mov_b32_e32 v90, v7
	v_mov_b32_e32 v91, v8
	v_mov_b32_e32 v92, v6
	v_mov_b32_e32 v93, v9
	v_pk_add_f32 v[80:81], v[86:87], v[88:89]
	v_pk_add_f32 v[74:75], v[98:99], v[76:77]
	v_pk_add_f32 v[82:83], v[90:91], v[92:93]
	v_pk_add_f32 v[74:75], v[74:75], v[80:81]
	v_pk_add_f32 v[78:79], v[82:83], v[82:83] op_sel:[0,1] op_sel_hi:[1,0]
	v_pk_add_f32 v[74:75], v[74:75], v[74:75] op_sel:[0,1] op_sel_hi:[1,0]
	s_waitcnt vmcnt(1)
	v_add_f32_e32 v94, v14, v15
	s_waitcnt vmcnt(0)
	v_mov_b32_e32 v95, v4
	v_add_f32_e32 v96, v16, v17
	v_mov_b32_e32 v97, v5
	v_mov_b32_e32 v79, v3
	v_mov_b32_e32 v75, v2
	v_pk_add_f32 v[84:85], v[94:95], v[96:97]
	v_pk_add_f32 v[74:75], v[74:75], v[78:79]
	s_nop 0
	v_pk_add_f32 v[74:75], v[74:75], v[84:85]
	s_nop 0
	v_add_f32_e32 v65, v74, v75
	ds_bpermute_b32 v74, v1, v65
	s_waitcnt lgkmcnt(0)
	v_add_f32_e32 v65, v65, v74
	ds_bpermute_b32 v74, v58, v65
	s_waitcnt lgkmcnt(0)
	v_add_f32_e32 v65, v65, v74
	ds_bpermute_b32 v74, v59, v65
	s_waitcnt lgkmcnt(0)
	v_add_f32_e32 v65, v65, v74
	ds_bpermute_b32 v74, v60, v65
	s_waitcnt lgkmcnt(0)
	v_add_f32_e32 v65, v65, v74
	ds_bpermute_b32 v74, v61, v65
	s_waitcnt lgkmcnt(0)
	v_add_f32_e32 v65, v65, v74
	ds_bpermute_b32 v74, v62, v65
	s_waitcnt lgkmcnt(0)
	v_add_f32_e32 v65, v65, v74
	v_fmamk_f32 v23, v65, 0xba000000, v23
	v_fmamk_f32 v22, v65, 0xba000000, v22
	v_fmamk_f32 v25, v65, 0xba000000, v25
	v_fmac_f32_e32 v24, 0xba000000, v65
	v_fmamk_f32 v7, v65, 0xba000000, v7
	v_fmamk_f32 v6, v65, 0xba000000, v6
	v_fmamk_f32 v9, v65, 0xba000000, v9
	v_fmac_f32_e32 v8, 0xba000000, v65
	v_fmamk_f32 v31, v65, 0xba000000, v31
	v_fmamk_f32 v27, v65, 0xba000000, v27
	v_fmamk_f32 v33, v65, 0xba000000, v33
	v_fmamk_f32 v75, v65, 0xba000000, v29
	v_fmac_f32_e32 v30, 0xba000000, v65
	v_fmac_f32_e32 v26, 0xba000000, v65
	v_fmamk_f32 v32, v65, 0xba000000, v32
	v_fmamk_f32 v74, v65, 0xba000000, v28
	v_fmamk_f32 v77, v65, 0xba000000, v15
	v_fmamk_f32 v76, v65, 0xba000000, v14
	v_fmamk_f32 v79, v65, 0xba000000, v13
	v_fmamk_f32 v78, v65, 0xba000000, v12
	v_pk_mul_f32 v[12:13], v[24:25], v[24:25]
	v_pk_mul_f32 v[14:15], v[22:23], v[22:23]
	v_pk_mul_f32 v[28:29], v[8:9], v[8:9]
	v_pk_mul_f32 v[80:81], v[6:7], v[6:7]
	v_mov_b32_e32 v84, v31
	v_mov_b32_e32 v85, v27
	v_mov_b32_e32 v88, v33
	v_mov_b32_e32 v89, v75
	v_mov_b32_e32 v82, v30
	v_mov_b32_e32 v83, v26
	v_mov_b32_e32 v86, v32
	v_mov_b32_e32 v87, v74
	v_pk_mov_b32 v[98:99], v[14:15], v[12:13] op_sel:[1,0]
	v_mov_b32_e32 v15, v13
	v_pk_mov_b32 v[12:13], v[80:81], v[28:29] op_sel:[1,0]
	v_mov_b32_e32 v81, v29
	v_pk_mul_f32 v[28:29], v[84:85], v[84:85]
	v_pk_mul_f32 v[84:85], v[88:89], v[88:89]
	v_fmamk_f32 v18, v65, 0xba000000, v18
	v_fmac_f32_e32 v20, 0xba000000, v65
	v_pk_fma_f32 v[28:29], v[82:83], v[82:83], v[28:29]
	v_pk_fma_f32 v[82:83], v[86:87], v[86:87], v[84:85]
	v_fmamk_f32 v19, v65, 0xba000000, v19
	v_fmamk_f32 v21, v65, 0xba000000, v21
	v_mul_f32_e32 v90, v18, v18
	v_mul_f32_e32 v92, v20, v20
	v_pk_add_f32 v[14:15], v[98:99], v[14:15]
	v_pk_add_f32 v[28:29], v[28:29], v[82:83]
	v_fmamk_f32 v11, v65, 0xba000000, v11
	v_fmac_f32_e32 v10, 0xba000000, v65
	v_pk_fma_f32 v[88:89], v[18:19], v[18:19], v[90:91] op_sel_hi:[1,1,0]
	v_pk_fma_f32 v[90:91], v[20:21], v[20:21], v[92:93] op_sel_hi:[1,1,0]
	v_pk_add_f32 v[14:15], v[14:15], v[14:15] op_sel_hi:[0,1]
	v_pk_add_f32 v[28:29], v[28:29], v[28:29] op_sel_hi:[0,1]
	v_mul_f32_e32 v88, v10, v10
	v_mul_f32_e32 v90, v11, v11
	v_mul_f32_e32 v14, v78, v78
	v_mul_f32_e32 v28, v79, v79
	v_fmac_f32_e32 v16, 0xba000000, v65
	v_pk_add_f32 v[12:13], v[12:13], v[80:81]
	v_pk_add_f32 v[80:81], v[88:89], v[90:91]
	v_pk_add_f32 v[14:15], v[14:15], v[28:29]
	v_fmamk_f32 v17, v65, 0xba000000, v17
	v_mul_f32_e32 v94, v76, v76
	v_mul_f32_e32 v96, v16, v16
	v_pk_add_f32 v[14:15], v[80:81], v[14:15]
	v_fmamk_f32 v3, v65, 0xba000000, v3
	v_fmac_f32_e32 v2, 0xba000000, v65
	v_fmamk_f32 v5, v65, 0xba000000, v5
	v_fmamk_f32 v4, v65, 0xba000000, v4
	v_pk_fma_f32 v[92:93], v[76:77], v[76:77], v[94:95] op_sel_hi:[1,1,0]
	v_pk_fma_f32 v[94:95], v[16:17], v[16:17], v[96:97] op_sel_hi:[1,1,0]
	v_pk_add_f32 v[12:13], v[12:13], v[12:13] op_sel_hi:[0,1]
	v_pk_add_f32 v[14:15], v[14:15], v[14:15] op_sel_hi:[0,1]
	v_mul_f32_e32 v92, v2, v2
	v_mul_f32_e32 v94, v3, v3
	v_mul_f32_e32 v12, v4, v4
	v_mul_f32_e32 v14, v5, v5
	v_pk_add_f32 v[82:83], v[92:93], v[94:95]
	v_pk_add_f32 v[12:13], v[12:13], v[14:15]
	s_nop 0
	v_pk_add_f32 v[12:13], v[82:83], v[12:13]
	s_nop 0
	v_add_f32_e32 v12, v12, v13
	ds_bpermute_b32 v13, v1, v12
	s_waitcnt lgkmcnt(0)
; __device__ __forceinline__ unsigned cvt_pk_bf16(float lo, float hi) { unsigned r; asm volatile("v_cvt_pk_bf16_f32 %0, %1, %2" : "=v"(r) : "v"(lo), "v"(hi)); return r; }
; __device__ __forceinline__ void ln_row(const float* yrow, const float* g, const float* b, float* of, bf16_t* ob, int lane) {
;     ...
;     const float rstd = 1.0f / sqrtf(wave_sum(s2) * (1.f / D) + LN_EPS);
; #pragma unroll
;     for (int j = 0; j < 8; ++j) {
;         const f32x4 gg = *(const f32x4*)(g + 4 * lane + 256 * j), bb = *(const f32x4*)(b + 4 * lane + 256 * j);
;         const f32x4 o = v[j] * rstd * gg + bb;
;         if (of) __builtin_nontemporal_store(o, (f32x4*)(of + 4 * lane + 256 * j));
;         if (ob) { u32x2 w; w.x = cvt_pk_bf16(o[0], o[1]); w.y = cvt_pk_bf16(o[2], o[3]); *(u32x2*)(ob + 4 * lane + 256 * j) = w; }
;     }
	v_add_f32_e32 v12, v12, v13
	ds_bpermute_b32 v13, v58, v12
	s_waitcnt lgkmcnt(0)
	v_add_f32_e32 v12, v12, v13
	ds_bpermute_b32 v13, v59, v12
	s_waitcnt lgkmcnt(0)
	v_add_f32_e32 v12, v12, v13
	ds_bpermute_b32 v13, v60, v12
	s_waitcnt lgkmcnt(0)
	v_add_f32_e32 v12, v12, v13
	ds_bpermute_b32 v13, v61, v12
	s_waitcnt lgkmcnt(0)
	v_add_f32_e32 v12, v12, v13
	ds_bpermute_b32 v13, v62, v12
	s_waitcnt lgkmcnt(0)
	v_add_f32_e32 v12, v12, v13
	v_fmamk_f32 v12, v12, 0x3a000000, v63
	v_mul_f32_e32 v13, 0x4f800000, v12
	v_cmp_gt_f32_e32 vcc, s2, v12
	s_nop 1
	v_cndmask_b32_e32 v12, v12, v13, vcc
	v_sqrt_f32_e32 v13, v12
	s_nop 0
	v_add_u32_e32 v14, -1, v13
	v_add_u32_e32 v15, 1, v13
	v_fma_f32 v28, -v14, v13, v12
	v_fma_f32 v29, -v15, v13, v12
	v_cmp_ge_f32_e64 s[0:1], 0, v28
	s_nop 1
	v_cndmask_b32_e64 v13, v13, v14, s[0:1]
	v_cmp_lt_f32_e64 s[0:1], 0, v29
	s_nop 1
	v_cndmask_b32_e64 v13, v13, v15, s[0:1]
	v_mul_f32_e32 v14, 0x37800000, v13
	v_cndmask_b32_e32 v13, v13, v14, vcc
	v_cmp_class_f32_e32 vcc, v12, v64
	s_nop 1
	v_cndmask_b32_e32 v12, v13, v12, vcc
	v_div_scale_f32 v13, s[0:1], v12, v12, 1.0
	v_rcp_f32_e32 v15, v13
	v_div_scale_f32 v14, vcc, 1.0, v12, 1.0
	v_fma_f32 v28, -v13, v15, 1.0
	v_fmac_f32_e32 v15, v28, v15
	v_mul_f32_e32 v28, v14, v15
	v_fma_f32 v29, -v13, v28, v14
	v_fmac_f32_e32 v28, v29, v15
	v_fma_f32 v13, -v13, v28, v14
	v_div_fmas_f32 v13, v13, v15, v28
	v_div_fixup_f32 v80, v13, v12, 1.0
	v_pk_mul_f32 v[12:13], v[30:31], v[80:81] op_sel_hi:[1,0]
	v_pk_mul_f32 v[14:15], v[32:33], v[80:81] op_sel_hi:[1,0]
	s_nop 0
	v_pk_fma_f32 v[12:13], v[66:67], v[12:13], v[70:71]
	v_pk_fma_f32 v[14:15], v[68:69], v[14:15], v[72:73]
	v_cvt_pk_bf16_f32 v12, v12, v13
	v_pk_mul_f32 v[26:27], v[26:27], v[80:81] op_sel_hi:[1,0]
	v_cvt_pk_bf16_f32 v13, v14, v15
	global_store_dwordx2 v[56:57], v[12:13], off
	s_nop 1
	v_mov_b32_e32 v12, v108
	v_mov_b32_e32 v13, v109
	v_mov_b32_e32 v14, v110
	v_mov_b32_e32 v15, v111
	v_mov_b32_e32 v28, v112
	v_mov_b32_e32 v29, v113
	v_mov_b32_e32 v30, v114
	v_mov_b32_e32 v31, v115
	v_pk_mul_f32 v[32:33], v[74:75], v[80:81] op_sel_hi:[1,0]
	v_pk_mul_f32 v[22:23], v[22:23], v[80:81] op_sel_hi:[1,0]
	v_pk_mul_f32 v[24:25], v[24:25], v[80:81] op_sel_hi:[1,0]
	v_pk_mul_f32 v[18:19], v[18:19], v[80:81] op_sel_hi:[1,0]
	v_pk_mul_f32 v[20:21], v[20:21], v[80:81] op_sel_hi:[1,0]
	v_pk_mul_f32 v[10:11], v[10:11], v[80:81] op_sel_hi:[1,0]
	v_pk_mul_f32 v[6:7], v[6:7], v[80:81] op_sel_hi:[1,0]
	v_pk_mul_f32 v[8:9], v[8:9], v[80:81] op_sel_hi:[1,0]
	v_pk_mul_f32 v[16:17], v[16:17], v[80:81] op_sel_hi:[1,0]
	v_pk_mul_f32 v[2:3], v[2:3], v[80:81] op_sel_hi:[1,0]
	v_pk_mul_f32 v[4:5], v[4:5], v[80:81] op_sel_hi:[1,0]
	s_nop 0
	v_pk_fma_f32 v[12:13], v[12:13], v[26:27], v[28:29]
	v_pk_fma_f32 v[14:15], v[14:15], v[32:33], v[30:31]
	v_cvt_pk_bf16_f32 v12, v12, v13
	s_nop 0
	v_cvt_pk_bf16_f32 v13, v14, v15
	global_store_dwordx2 v[56:57], v[12:13], off offset:512
	s_nop 1
	v_mov_b32_e32 v12, v116
	v_mov_b32_e32 v13, v117
	v_mov_b32_e32 v14, v118
	v_mov_b32_e32 v15, v119
	v_mov_b32_e32 v26, v120
	v_mov_b32_e32 v27, v121
	v_mov_b32_e32 v28, v122
	v_mov_b32_e32 v29, v123
	s_nop 0
	v_pk_fma_f32 v[12:13], v[12:13], v[22:23], v[26:27]
	v_pk_fma_f32 v[14:15], v[14:15], v[24:25], v[28:29]
	v_cvt_pk_bf16_f32 v12, v12, v13
	s_nop 0
	v_cvt_pk_bf16_f32 v13, v14, v15
	global_store_dwordx2 v[56:57], v[12:13], off offset:1024
	s_nop 1
	v_mov_b32_e32 v12, v124
	v_mov_b32_e32 v13, v125
	v_mov_b32_e32 v14, v126
	v_mov_b32_e32 v15, v127
	v_mov_b32_e32 v22, v128
	v_mov_b32_e32 v23, v129
	v_mov_b32_e32 v24, v130
	v_mov_b32_e32 v25, v131
	s_nop 0
	v_pk_fma_f32 v[12:13], v[12:13], v[18:19], v[22:23]
	v_pk_fma_f32 v[14:15], v[14:15], v[20:21], v[24:25]
	v_cvt_pk_bf16_f32 v12, v12, v13
	v_pk_mul_f32 v[22:23], v[78:79], v[80:81] op_sel_hi:[1,0]
	v_cvt_pk_bf16_f32 v13, v14, v15
	global_store_dwordx2 v[56:57], v[12:13], off offset:1536
	s_nop 1
	v_mov_b32_e32 v12, v132
	v_mov_b32_e32 v13, v133
	v_mov_b32_e32 v14, v134
	v_mov_b32_e32 v15, v135
	v_mov_b32_e32 v18, v136
	v_mov_b32_e32 v19, v137
	v_mov_b32_e32 v20, v138
	v_mov_b32_e32 v21, v139
	s_nop 0
	v_pk_fma_f32 v[10:11], v[12:13], v[10:11], v[18:19]
	v_pk_fma_f32 v[14:15], v[14:15], v[22:23], v[20:21]
	v_cvt_pk_bf16_f32 v10, v10, v11
	s_nop 0
	v_cvt_pk_bf16_f32 v11, v14, v15
	global_store_dwordx2 v[56:57], v[10:11], off offset:2048
	s_nop 1
	v_mov_b32_e32 v10, v140
	v_mov_b32_e32 v11, v141
	v_mov_b32_e32 v12, v142
	v_mov_b32_e32 v13, v143
	v_mov_b32_e32 v18, v144
	v_mov_b32_e32 v19, v145
	v_mov_b32_e32 v20, v146
	v_mov_b32_e32 v21, v147
	v_pk_mul_f32 v[14:15], v[76:77], v[80:81] op_sel_hi:[1,0]
	s_nop 0
	v_pk_fma_f32 v[6:7], v[6:7], v[10:11], v[18:19]
	v_pk_fma_f32 v[8:9], v[8:9], v[12:13], v[20:21]
	v_cvt_pk_bf16_f32 v6, v6, v7
	s_nop 0
	v_cvt_pk_bf16_f32 v7, v8, v9
	global_store_dwordx2 v[56:57], v[6:7], off offset:2560
	s_nop 1
	v_mov_b32_e32 v6, v148
	v_mov_b32_e32 v7, v149
	v_mov_b32_e32 v8, v150
	v_mov_b32_e32 v9, v151
	v_mov_b32_e32 v10, v152
	v_mov_b32_e32 v11, v153
	v_mov_b32_e32 v12, v154
	v_mov_b32_e32 v13, v155
	s_nop 0
	v_pk_fma_f32 v[6:7], v[14:15], v[6:7], v[10:11]
	v_pk_fma_f32 v[8:9], v[16:17], v[8:9], v[12:13]
	v_cvt_pk_bf16_f32 v6, v6, v7
	s_nop 0
	v_cvt_pk_bf16_f32 v7, v8, v9
	global_store_dwordx2 v[56:57], v[6:7], off offset:3072
	s_nop 1
	v_mov_b32_e32 v6, v156
	v_mov_b32_e32 v7, v157
	v_mov_b32_e32 v8, v158
	v_mov_b32_e32 v9, v159
	v_mov_b32_e32 v10, v160
	v_mov_b32_e32 v11, v161
	v_mov_b32_e32 v12, v162
	v_mov_b32_e32 v13, v163
	s_nop 0
	v_pk_fma_f32 v[2:3], v[2:3], v[6:7], v[10:11]
	v_pk_fma_f32 v[4:5], v[4:5], v[8:9], v[12:13]
	v_cvt_pk_bf16_f32 v2, v2, v3
	s_nop 0
	v_cvt_pk_bf16_f32 v3, v4, v5
	global_store_dwordx2 v[56:57], v[2:3], off offset:3584
	s_nop 1
	v_lshl_add_u64 v[56:57], v[56:57], 0, s[8:9]
	s_cbranch_scc0 .LBB0_73

; __device__ __forceinline__ float bflo(unsigned w) { return __uint_as_float(w << 16); }
; __device__ __forceinline__ float bfhi(unsigned w) { return __uint_as_float(w & 0xffff0000u); }
; __global__ void __launch_bounds__(NTHREADS, 2) fwd_kernel(Params P) {
;     ...
;     if (PHON(5)) for (int r = gw; r < MR; r += NGW) {
;         const bf16_t* zr = Z + (size_t)r * NZ + 1024;
;         float v[16]; float s = 0.f;
; #pragma unroll
;         for (int h = 0; h < 2; ++h) { const u32x4 w = *(const u32x4*)(zr + 8 * lane + 512 * h);
;             v[8 * h + 0] = bflo(w.x); v[8 * h + 1] = bfhi(w.x); v[8 * h + 2] = bflo(w.y); v[8 * h + 3] = bfhi(w.y); v[8 * h + 4] = bflo(w.z); v[8 * h + 5] = bfhi(w.z); v[8 * h + 6] = bflo(w.w); v[8 * h + 7] = bfhi(w.w); }
.LBB0_570:
	s_cmpk_lt_i32 s30, 0x2080
	s_cselect_b64 s[0:1], -1, 0
	v_writelane_b32 v255, s0, 31
	s_cmpk_gt_i32 s30, 0x207f
	s_nop 0
	v_writelane_b32 v255, s1, 32
	s_cbranch_scc1 .LBB0_577
	s_cmp_lt_u32 s34, 8
	s_cbranch_scc1 .LBB0_577
	s_sub_i32 s30, s30, 64
	s_sub_i32 s36, s36, 64
	v_mbcnt_hi_u32_b32 v0, -1, v179
	v_and_b32_e32 v2, 64, v0
	v_add_u32_e32 v2, 64, v2
	v_xor_b32_e32 v3, 1, v0
	v_cmp_lt_i32_e32 vcc, v3, v2
	v_readlane_b32 s8, v254, 0
	v_readlane_b32 s9, v254, 1
	v_cndmask_b32_e32 v3, v0, v3, vcc
	v_lshlrev_b32_e32 v9, 2, v3
	v_xor_b32_e32 v3, 2, v0
	v_cmp_lt_i32_e32 vcc, v3, v2
	v_readlane_b32 s10, v254, 2
	v_readlane_b32 s11, v254, 3
	v_cndmask_b32_e32 v3, v0, v3, vcc
	v_lshlrev_b32_e32 v26, 2, v3
	v_xor_b32_e32 v3, 4, v0
	v_cmp_lt_i32_e32 vcc, v3, v2
	v_readlane_b32 s12, v254, 4
	v_readlane_b32 s13, v254, 5
	v_cndmask_b32_e32 v3, v0, v3, vcc
	v_lshlrev_b32_e32 v27, 2, v3
	v_xor_b32_e32 v3, 8, v0
	v_cmp_lt_i32_e32 vcc, v3, v2
	v_readlane_b32 s14, v254, 6
	v_readlane_b32 s15, v254, 7
	v_cndmask_b32_e32 v3, v0, v3, vcc
	s_mov_b64 s[8:9], s[12:13]
	v_lshlrev_b32_e32 v28, 2, v3
	v_xor_b32_e32 v3, 16, v0
	s_mov_b64 s[10:11], s[14:15]
	v_cmp_lt_i32_e32 vcc, v3, v2
	s_add_u32 s2, s10, 0x4b10000
	s_addc_u32 s3, s11, 0
	v_cndmask_b32_e32 v3, v0, v3, vcc
	s_lshl_b64 s[0:1], s[30:31], 11
	v_lshlrev_b32_e32 v29, 2, v3
	v_xor_b32_e32 v3, 32, v0
	v_readlane_b32 s8, v254, 11
	s_add_u32 s6, s92, s0
	v_cmp_lt_i32_e32 vcc, v3, v2
	v_readlane_b32 s9, v254, 12
	v_readlane_b32 s14, v254, 17
	v_readlane_b32 s15, v254, 18
	v_readlane_b32 s16, v254, 19
	v_readlane_b32 s17, v254, 20
	v_readlane_b32 s18, v254, 21
	v_readlane_b32 s19, v254, 22
	v_readlane_b32 s20, v254, 23
	v_readlane_b32 s21, v254, 24
	s_addc_u32 s7, s93, s1
	s_ashr_i32 s37, s36, 31
	v_cndmask_b32_e32 v0, v0, v3, vcc
	v_readlane_b32 s10, v254, 13
	v_readlane_b32 s22, v254, 25
	v_readlane_b32 s23, v254, 26
	s_mov_b64 s[14:15], s[18:19]
	s_mov_b64 s[16:17], s[20:21]
	s_lshl_b64 s[8:9], s[36:37], 11
	s_mul_i32 s1, s30, 0x5800
	v_mov_b32_e32 v1, 0
	v_lshlrev_b32_e32 v30, 2, v0
	v_lshlrev_b32_e32 v0, 5, v237
	v_readlane_b32 s11, v254, 14
	s_mov_b64 s[18:19], s[22:23]
	s_mul_hi_i32 s0, s30, 0x5800
	s_add_u32 s10, s92, s1
	v_lshlrev_b32_e32 v8, 3, v237
	s_mov_b32 s5, 0
	v_lshl_add_u64 v[10:11], s[14:15], 0, v[0:1]
	v_lshl_add_u64 v[12:13], s[16:17], 0, v[0:1]
	v_mov_b32_e32 v177, v1
	s_addc_u32 s11, s93, s0
	s_mul_hi_i32 s16, s36, 0x5800
	s_mul_i32 s17, s36, 0x5800
	v_mov_b32_e32 v31, 0x3727c5ac
	s_mov_b32 s18, 0xf800000
	v_mov_b32_e32 v32, 0x260
	s_mov_b32 s19, s30
	v_readlane_b32 s12, v254, 15
	v_readlane_b32 s13, v254, 16
	global_load_dwordx4 v[60:63], v[12:13], off
	global_load_dwordx4 v[64:67], v[10:11], off
	global_load_dwordx4 v[68:71], v[10:11], off offset:16
	global_load_dwordx4 v[72:75], v[12:13], off offset:16
	global_load_dwordx4 v[76:79], v[12:13], off offset:2048
	global_load_dwordx4 v[80:83], v[10:11], off offset:2048
	global_load_dwordx4 v[84:87], v[10:11], off offset:2064
	global_load_dwordx4 v[88:91], v[12:13], off offset:2064
	s_waitcnt vmcnt(0)
	s_branch .LBB0_573

; #define LAS __attribute__((address_space(3)))
; __global__ void __launch_bounds__(NTHREADS, 2) fwd_kernel(Params P) {
;     ...
;     if (PHON(6)) {
;         LAS bf16_t* XCB = (LAS bf16_t*)lds;
;         LAS float* AARR = (LAS float*)lds;
;         LAS float* XCF = (LAS float*)(lds + 65536);
;         for (int it = bid; it < 65 * 8; it += G) {
;             const int c = it >> 3, k = it & 7; const bool smp = (c == 64);
;             const int r0 = c * 128, ch0 = k * 128;
;             int lane_o = lane; asm volatile("" : "+v"(lane_o));
;             const int fr = lane_o & 15, fq = lane_o >> 4, rh = wave >> 2, cq = wave & 3;
;             bf16x8 wfr[4][4];
;             {
;                 const bf16_t* wb = WLRU + (size_t)k * 256 * 128;
; #pragma unroll
;                 for (int ct = 0; ct < 4; ++ct)
; #pragma unroll
;                     for (int ks = 0; ks < 4; ++ks) wfr[ct][ks] = *(const bf16x8*)(wb + (size_t)((ct >> 1) * 128 + 32 * cq + 16 * (ct & 1) + fr) * 128 + ks * 32 + fq * 8);
;             }
;             LAS float* prm = (LAS float*)(lds + 131072 + 4096);
;             if (tid < 128) { prm[tid] = P.in[I_LBA][ch0 + tid]; prm[128 + tid] = P.in[I_LBX][ch0 + tid]; prm[256 + tid] = __logf(1.0f + __expf(-P.in[I_LAM][ch0 + tid])); }
;             {
;                 const int c4 = (tid & 31) * 4, rg = tid >> 5;
;                 const int ch = ch0 + c4;
;                 const f32x4 w0 = *(const f32x4*)(P.in[I_CONVW] + 0 * BW + ch), w1 = *(const f32x4*)(P.in[I_CONVW] + 1 * BW + ch), w2 = *(const f32x4*)(P.in[I_CONVW] + 2 * BW + ch), w3 = *(const f32x4*)(P.in[I_CONVW] + 3 * BW + ch);
;                 const f32x4 cb = *(const f32x4*)(P.in[I_CONVB] + ch);
.LBB0_577:
	s_lshl_b32 s36, s94, 3
	v_writelane_b32 v255, s36, 16
	s_cmpk_gt_i32 s34, 0x207
	v_lshlrev_b32_e32 v183, 2, v178
	v_writelane_b32 v255, s37, 17
	v_lshrrev_b32_e32 v177, 5, v178
	s_cbranch_scc1 .LBB0_626
	v_readlane_b32 s0, v254, 45
	v_readlane_b32 s8, v254, 53
	v_readlane_b32 s9, v254, 54
	v_readlane_b32 s10, v254, 55
	v_readlane_b32 s11, v254, 56
	v_readlane_b32 s12, v254, 57
	v_readlane_b32 s13, v254, 58
	v_readlane_b32 s14, v254, 59
	v_readlane_b32 s15, v254, 60
	v_mov_b32_e32 v0, s10
	v_mov_b32_e32 v1, s11
	s_add_u32 s33, s92, 0xcc00000
	v_readlane_b32 s8, v254, 61
	s_addc_u32 s35, s93, 0
	s_lshl_b32 s50, s56, 5
	s_add_i32 s51, 0, 0x21000
	v_readlane_b32 s10, v254, 63
	v_readlane_b32 s11, v255, 0
	s_add_u32 s46, s10, 0x1000
	s_addc_u32 s47, s11, 0
	s_add_u32 s62, s10, 0x2000
	v_readlane_b32 s16, v255, 5
	v_readlane_b32 s17, v255, 6
	v_readlane_b32 s18, v255, 7
	v_readlane_b32 s19, v255, 8
	v_readlane_b32 s20, v255, 9
	v_readlane_b32 s21, v255, 10
	v_readlane_b32 s22, v255, 11
	v_readlane_b32 s23, v255, 12
	s_addc_u32 s63, s11, 0
	v_readlane_b32 s4, v254, 49
	v_readlane_b32 s5, v254, 50
	s_movk_i32 s0, 0x80
	s_add_u32 s64, s10, 0x3000
	v_readlane_b32 s16, v254, 0
	v_readlane_b32 s6, v254, 51
	v_readlane_b32 s7, v254, 52
	v_cmp_gt_u32_e64 s[4:5], s0, v178
	s_movk_i32 s0, 0x7f
	s_addc_u32 s65, s11, 0
	s_add_i32 s84, 0, 0x10000
	v_readlane_b32 s22, v254, 6
	v_cmp_lt_u32_e64 s[6:7], s0, v178
	v_readlane_b32 s23, v254, 7
	s_add_u32 s36, s22, 0x4900000
	v_readlane_b32 s0, v255, 26
	s_addc_u32 s37, s23, 0
	s_lshr_b32 s0, s0, 2
	s_and_b32 s85, s0, 0x3fffffc0
	s_add_u32 s26, s92, 0x2b1f0600
	s_addc_u32 s27, s93, 0
	s_add_u32 s96, s92, 0x2b270600
	s_addc_u32 s97, s93, 0
	v_and_b32_e32 v112, 0x7c, v183
	s_add_u32 s28, s92, 0x2b2f0600
	v_readlane_b32 s1, v254, 46
	v_lshlrev_b32_e32 v114, 1, v112
	s_addc_u32 s29, s93, 0
	v_mov_b32_e32 v115, 0
	s_add_i32 s0, 0, 0x20000
	v_add_u32_e32 v149, s0, v183
	v_lshl_add_u64 v[4:5], s[92:93], 0, v[114:115]
	s_mov_b64 s[0:1], 0x237a0000
	v_lshrrev_b32_e32 v3, 2, v178
	v_lshl_add_u64 v[118:119], v[4:5], 0, s[0:1]
	s_mov_b64 s[0:1], 0x257a0000
	v_and_b32_e32 v146, 0xf8, v3
	v_lshl_add_u64 v[120:121], v[4:5], 0, s[0:1]
	s_movk_i32 s0, 0x7b
	v_cmp_lt_u32_e64 s[66:67], s0, v146
	v_lshrrev_b32_e32 v17, 5, v178
	s_mov_b32 s0, 0x2c000
	v_mov_b64_e32 v[4:5], s[92:93]
	v_readlane_b32 s2, v254, 47
	v_mad_u64_u32 v[4:5], s[0:1], v17, s0, v[4:5]
	s_movk_i32 s2, 0x7c
	v_readlane_b32 s12, v255, 1
	v_readlane_b32 s13, v255, 2
	v_readlane_b32 s14, v255, 3
	v_readlane_b32 s15, v255, 4
	v_readlane_b32 s17, v254, 1
	v_readlane_b32 s18, v254, 2
	v_readlane_b32 s19, v254, 3
	v_or_b32_e32 v153, 3, v146
	v_or_b32_e32 v155, 5, v146
	v_or_b32_e32 v156, 6, v146
	v_or_b32_e32 v157, 7, v3
	s_mov_b64 s[0:1], 0x19db1800
	v_and_b32_e32 v19, 31, v178
	v_cmp_lt_u32_e64 s[44:45], s2, v146
	v_cmp_lt_u32_e64 s[12:13], s2, v153
	v_cmp_lt_u32_e64 s[14:15], s2, v155
	v_cmp_lt_u32_e64 s[16:17], s2, v156
	v_lshl_add_u64 v[122:123], v[4:5], 0, s[0:1]
	v_cmp_lt_u32_e64 s[18:19], s2, v157
	v_lshlrev_b32_e32 v4, 3, v19
	s_movk_i32 s0, 0x880
	s_mov_b32 s2, 0x18000
	v_mad_u32_u24 v159, v177, s0, v4
	v_mad_u64_u32 v[126:127], s[0:1], v17, s2, v[0:1]
	v_or_b32_e32 v0, 0x1000, v183
	v_readlane_b32 s3, v254, 48
	v_lshrrev_b32_e32 v148, 7, v178
	v_and_b32_e32 v2, 0x7f, v178
	v_lshrrev_b32_e32 v160, 7, v0
	v_lshl_add_u32 v168, v0, 2, s84
	v_lshlrev_b32_e32 v0, 4, v19
	v_lshl_or_b32 v116, v148, 12, v2
	s_add_i32 s3, 0, 0x20800
	v_or_b32_e32 v151, 1, v146
	v_or_b32_e32 v152, 2, v146
	v_or_b32_e32 v154, 4, v146
	v_mov_b64_e32 v[4:5], s[22:23]
	v_add_u32_e32 v1, 0x1800, v183
	v_lshl_or_b32 v174, v177, 12, v0
	v_lshlrev_b32_e32 v0, 2, v2
	v_lshl_add_u32 v6, v112, 2, s84
	v_add_u32_e32 v7, 0, v114
	v_readlane_b32 s20, v254, 4
	v_readlane_b32 s21, v254, 5
	s_add_u32 s30, s92, 0x277a0000
	v_lshlrev_b32_e32 v8, 9, v146
	v_mul_u32_u24_e32 v9, 0x110, v146
	v_lshlrev_b32_e32 v10, 9, v151
	v_lshlrev_b32_e32 v11, 9, v152
	v_lshlrev_b32_e32 v12, 9, v153
	v_lshlrev_b32_e32 v13, 9, v154
	v_lshlrev_b32_e32 v14, 9, v155
	v_lshlrev_b32_e32 v15, 9, v156
	v_lshlrev_b32_e32 v3, 9, v157
	v_mul_u32_u24_e32 v16, 0x110, v157
	v_add_u32_e32 v18, 0x800, v183
	v_mad_u64_u32 v[124:125], s[0:1], v17, s2, v[4:5]
	v_lshrrev_b32_e32 v161, 7, v1
	v_or_b32_e32 v4, 0x2000, v183
	v_add_u32_e32 v5, 0x2800, v183
	v_or_b32_e32 v17, 0x3000, v183
	v_add_u32_e32 v20, 0x3800, v183
	v_lshl_add_u32 v169, v1, 2, s84
	v_or_b32_e32 v128, 0x100, v116
	v_or_b32_e32 v130, 0x200, v116
	v_or_b32_e32 v132, 0x300, v116
	v_or_b32_e32 v134, 0x400, v116
	v_or_b32_e32 v136, 0x500, v116
	v_or_b32_e32 v138, 0x600, v116
	v_or_b32_e32 v140, 0x700, v116
	v_lshl_or_b32 v1, v148, 14, v0
	v_add_u32_e32 v141, s51, v183
	v_add_u32_e32 v147, -3, v146
	v_add_u32_e32 v150, s3, v183
	s_addc_u32 s31, s93, 0
	v_lshrrev_b32_e32 v158, 7, v18
	v_lshrrev_b32_e32 v162, 7, v4
	v_lshrrev_b32_e32 v163, 7, v5
	v_lshrrev_b32_e32 v164, 7, v17
	v_lshrrev_b32_e32 v165, 7, v20
	v_add_u32_e32 v166, s84, v182
	v_lshl_add_u32 v167, v18, 2, s84
	v_lshl_add_u32 v170, v4, 2, s84
	v_lshl_add_u32 v171, v5, 2, s84
	v_lshl_add_u32 v172, v17, 2, s84
	v_lshl_add_u32 v173, v20, 2, s84
	v_mov_b32_e32 v113, v116
	v_mov_b32_e32 v117, v128
	v_mov_b32_e32 v129, v130
	v_mov_b32_e32 v131, v132
	v_mov_b32_e32 v133, v134
	v_mov_b32_e32 v135, v136
	v_mov_b32_e32 v137, v138
	v_mov_b32_e32 v139, v140
	v_add_u32_e32 v175, 0, v1
	v_add_u32_e32 v184, s3, v0
	s_mov_b32 s90, 0x8000
	v_add_u32_e32 v185, v6, v8
	v_add_u32_e32 v186, v6, v10
	v_add_u32_e32 v187, v6, v11
	v_add_u32_e32 v188, v6, v12
	v_add_u32_e32 v189, v6, v13
	v_add_u32_e32 v190, v6, v14
	v_add_u32_e32 v191, v6, v15
	v_add_u32_e32 v192, v6, v3
	v_add_u32_e32 v193, v7, v16
	v_lshlrev_b32_e32 v194, 2, v2
	v_mov_b32_e32 v195, 0x41b17218
	v_add_u32_e32 v196, v7, v9
	s_movk_i32 s91, 0x5800
	s_mov_b32 s2, s34
	s_mov_b32 s3, s34
	s_mov_b32 s87, 0
	v_cmp_lt_u32_e64 s[20:21], 31, v178
	v_cmp_eq_u32_e64 s[22:23], 3, v148
	v_readlane_b32 s9, v254, 62
	s_branch .LBB0_581
